# v83 plus the same MLA tile-loop treatment (descriptor kept in SGPRs, first K fragments read above the last two PV MFMAs) for the chunk-phase attention instance
# speedup vs baseline: 1.0119x; 1.0030x over previous
; #define LAS __attribute__((address_space(3)))
; __device__ __forceinline__ void unpack8(const u32x4 w, float (&f)[8]) { f[0] = bflo(w.x); f[1] = bfhi(w.x); f[2] = bflo(w.y); f[3] = bfhi(w.y); f[4] = bflo(w.z); f[5] = bfhi(w.z); f[6] = bflo(w.w); f[7] = bfhi(w.w); }
; __device__ __forceinline__ void lds_barrier() { asm volatile("s_waitcnt lgkmcnt(0)\n\ts_barrier" ::: "memory"); }
; __device__ __forceinline__ void mla_unit(const Frame& F, int h, int q0, int key0, int ntiles, int mode, int su) {
;     ...
;         for (int ks = 0; ks < 8; ++ks) { float x[8]; unpack8(*(const u32x4*)(qp + 16 * ks + 8 * hh), x);
; #pragma unroll
;             for (int j = 0; j < 8; ++j) x[j] *= SC;
;             Qf[ks] = __builtin_bit_cast(bf16x8, pack8(x)); }
; #pragma unroll
;         for (int ks = 8; ks < 12; ++ks) {
;             const int d0 = 16 * ks + 8 * hh;
;             const u32x4 own = *(const u32x4*)(qp + d0);
;             if (qr < SEQ) {
;                 const u32x4 par = *(const u32x4*)(qp + d0 + ((ks & 1) ? -16 : 16));
;                 float xo[8], xp[8], o[8]; unpack8(own, xo); unpack8(par, xp);
;                 const float* rp = rope + ((size_t)qr * 32 + ((ks - 8) >> 1) * 16 + 8 * hh) * 2;
; #pragma unroll
;                 for (int j = 0; j < 8; ++j) { const float cs = rp[2 * j], sn = rp[2 * j + 1]; o[j] = SC * ((ks & 1) ? (xp[j] * sn + xo[j] * cs) : (xo[j] * cs - xp[j] * sn)); }
;                 Qf[ks] = __builtin_bit_cast(bf16x8, pack8(o));
;             } else { float x[8]; unpack8(own, x);
; #pragma unroll
;                 for (int j = 0; j < 8; ++j) x[j] *= SC;
;                 Qf[ks] = __builtin_bit_cast(bf16x8, pack8(x)); }
;         }
;     ...
;     __syncthreads();
;     MLA_DMA(0, 0); MLA_DMA(1, 1);
;     asm volatile("s_waitcnt vmcnt(0)" ::: "memory");
;     lds_barrier();
;     const int krd = ql * MA_KSTR + 16 * hh;
;     const int vrd = (4 * hh + ((F.lane & 15) >> 2)) * MA_VSTR + (((F.lane >> 4) & 1) * 16 + (F.lane & 3) * 4) * 2;
;     f32x16 sA[2], sB[2];
;     {   const LAS unsigned char* kb = F.lds + MA_K_OFF + krd;
; #pragma unroll
;         for (int kt = 0; kt < 2; ++kt) { { const float nm = -m;
; #pragma unroll
;             for (int r = 0; r < 16; ++r) sA[kt][r] = nm; }
; #pragma unroll
;             for (int ks = 0; ks < 12; ++ks) { const bf16x8 kf = *(const LAS bf16x8*)(kb + kt * 32 * MA_KSTR + ks * 32); sA[kt] = MFMA32(kf, Qf[ks], sA[kt]); } } }
.LBB0_723:
	s_mov_b32 s8, 0x3dd53b94
	v_pk_mul_f32 v[114:115], v[64:65], s[8:9] op_sel_hi:[1,0]
	v_lshlrev_b32_e32 v64, 16, v40
	v_and_b32_e32 v65, 0xffff0000, v40
	v_lshlrev_b32_e32 v40, 16, v41
	v_and_b32_e32 v41, 0xffff0000, v41
	v_pk_mul_f32 v[40:41], v[40:41], s[8:9] op_sel_hi:[1,0]
	v_pk_mul_f32 v[108:109], v[66:67], s[8:9] op_sel_hi:[1,0]
	v_cvt_pk_bf16_f32 v137, v40, v41
	v_lshlrev_b32_e32 v40, 16, v36
	v_and_b32_e32 v41, 0xffff0000, v36
	v_lshlrev_b32_e32 v36, 16, v37
	v_and_b32_e32 v37, 0xffff0000, v37
	v_lshlrev_b32_e32 v66, 16, v42
	v_and_b32_e32 v67, 0xffff0000, v42
	v_lshlrev_b32_e32 v42, 16, v43
	v_and_b32_e32 v43, 0xffff0000, v43
	v_pk_mul_f32 v[36:37], v[36:37], s[8:9] op_sel_hi:[1,0]
	v_pk_mul_f32 v[42:43], v[42:43], s[8:9] op_sel_hi:[1,0]
	v_cvt_pk_bf16_f32 v141, v36, v37
	v_lshlrev_b32_e32 v36, 16, v28
	v_and_b32_e32 v37, 0xffff0000, v28
	v_lshlrev_b32_e32 v28, 16, v29
	v_and_b32_e32 v29, 0xffff0000, v29
	v_cvt_pk_bf16_f32 v139, v42, v43
	v_lshlrev_b32_e32 v42, 16, v38
	v_and_b32_e32 v43, 0xffff0000, v38
	v_lshlrev_b32_e32 v38, 16, v39
	v_and_b32_e32 v39, 0xffff0000, v39
	v_pk_mul_f32 v[28:29], v[28:29], s[8:9] op_sel_hi:[1,0]
	v_pk_mul_f32 v[38:39], v[38:39], s[8:9] op_sel_hi:[1,0]
	v_cvt_pk_bf16_f32 v145, v28, v29
	v_lshlrev_b32_e32 v28, 16, v24
	v_and_b32_e32 v29, 0xffff0000, v24
	v_lshlrev_b32_e32 v24, 16, v25
	v_and_b32_e32 v25, 0xffff0000, v25
	v_cvt_pk_bf16_f32 v143, v38, v39
	v_lshlrev_b32_e32 v38, 16, v30
	v_and_b32_e32 v39, 0xffff0000, v30
	v_lshlrev_b32_e32 v30, 16, v31
	v_and_b32_e32 v31, 0xffff0000, v31
	v_pk_mul_f32 v[24:25], v[24:25], s[8:9] op_sel_hi:[1,0]
	v_pk_mul_f32 v[30:31], v[30:31], s[8:9] op_sel_hi:[1,0]
	v_cvt_pk_bf16_f32 v149, v24, v25
	v_lshlrev_b32_e32 v24, 16, v20
	v_and_b32_e32 v25, 0xffff0000, v20
	v_lshlrev_b32_e32 v20, 16, v21
	v_and_b32_e32 v21, 0xffff0000, v21
	v_cvt_pk_bf16_f32 v147, v30, v31
	v_lshlrev_b32_e32 v30, 16, v26
	v_and_b32_e32 v31, 0xffff0000, v26
	v_pk_mul_f32 v[20:21], v[20:21], s[8:9] op_sel_hi:[1,0]
	v_pk_mul_f32 v[30:31], v[30:31], s[8:9] op_sel_hi:[1,0]
	v_lshlrev_b32_e32 v26, 16, v27
	v_and_b32_e32 v27, 0xffff0000, v27
	v_cvt_pk_bf16_f32 v153, v20, v21
	v_lshlrev_b32_e32 v20, 16, v12
	v_and_b32_e32 v21, 0xffff0000, v12
	v_lshlrev_b32_e32 v12, 16, v13
	v_and_b32_e32 v13, 0xffff0000, v13
	v_pk_mul_f32 v[26:27], v[26:27], s[8:9] op_sel_hi:[1,0]
	v_cvt_pk_bf16_f32 v150, v30, v31
	v_pk_mul_f32 v[30:31], v[12:13], s[8:9] op_sel_hi:[1,0]
	v_lshlrev_b32_e32 v12, 4, v116
	s_movk_i32 s0, 0x190
	v_cvt_pk_bf16_f32 v151, v26, v27
	v_lshlrev_b32_e32 v26, 16, v22
	v_and_b32_e32 v27, 0xffff0000, v22
	v_lshlrev_b32_e32 v22, 16, v23
	v_and_b32_e32 v23, 0xffff0000, v23
	s_waitcnt vmcnt(0)
	v_mad_u32_u24 v206, v74, s0, v12
	v_pk_mul_f32 v[28:29], v[28:29], s[8:9] op_sel_hi:[1,0]
	v_pk_mul_f32 v[22:23], v[22:23], s[8:9] op_sel_hi:[1,0]
	s_waitcnt lgkmcnt(0)
	s_barrier
	v_add_u32_e32 v207, 0, v206
	v_cvt_pk_bf16_f32 v148, v28, v29
	v_cvt_pk_bf16_f32 v155, v22, v23
	v_pk_mul_f32 v[28:29], v[20:21], s[8:9] op_sel_hi:[1,0]
	ds_read_b128 v[20:23], v207
	v_readlane_b32 s16, v254, 39
	v_readlane_b32 s30, v254, 53
	v_readlane_b32 s31, v254, 54
	v_pk_mul_f32 v[64:65], v[64:65], s[8:9] op_sel_hi:[1,0]
	v_pk_mul_f32 v[66:67], v[66:67], s[8:9] op_sel_hi:[1,0]
	v_readlane_b32 s17, v254, 40
	v_readlane_b32 s18, v254, 41
	v_readlane_b32 s19, v254, 42
	v_readlane_b32 s20, v254, 43
	v_readlane_b32 s21, v254, 44
	v_readlane_b32 s22, v254, 45
	v_readlane_b32 s23, v254, 46
	v_readlane_b32 s24, v254, 47
	v_readlane_b32 s25, v254, 48
	v_readlane_b32 s26, v254, 49
	v_readlane_b32 s27, v254, 50
	v_readlane_b32 s28, v254, 51
	v_readlane_b32 s29, v254, 52
	s_mov_b32 s30, s16
	s_mov_b32 s31, s16
	v_pk_mul_f32 v[110:111], v[70:71], s[8:9] op_sel_hi:[1,0]
	v_pk_mul_f32 v[112:113], v[68:69], s[8:9] op_sel_hi:[1,0]
	v_cvt_pk_bf16_f32 v136, v64, v65
	v_cvt_pk_bf16_f32 v138, v66, v67
	v_pk_mul_f32 v[24:25], v[24:25], s[8:9] op_sel_hi:[1,0]
	v_pk_mul_f32 v[26:27], v[26:27], s[8:9] op_sel_hi:[1,0]
	s_mov_b32 s17, s16
	s_mov_b32 s18, s16
	s_mov_b32 s19, s16
	s_mov_b32 s20, s16
	s_mov_b32 s21, s16
	s_mov_b32 s22, s16
	s_mov_b32 s23, s16
	s_mov_b32 s24, s16
	s_mov_b32 s25, s16
	s_mov_b32 s26, s16
	s_mov_b32 s27, s16
	s_mov_b32 s28, s16
	s_mov_b32 s29, s16
	v_mov_b64_e32 v[78:79], s[30:31]
	v_cvt_pk_bf16_f32 v152, v24, v25
	v_cvt_pk_bf16_f32 v154, v26, v27
	ds_read_b128 v[24:27], v207 offset:32
	v_mov_b64_e32 v[76:77], s[28:29]
	v_mov_b64_e32 v[74:75], s[26:27]
	v_mov_b64_e32 v[72:73], s[24:25]
	v_mov_b64_e32 v[70:71], s[22:23]
	v_mov_b64_e32 v[68:69], s[20:21]
	v_mov_b64_e32 v[66:67], s[18:19]
	v_mov_b64_e32 v[64:65], s[16:17]
	s_mov_b32 s0, s16
	v_lshlrev_b32_e32 v12, 16, v14
	s_waitcnt lgkmcnt(1)
	v_mfma_f32_32x32x16_bf16 v[80:95], v[20:23], v[136:139], v[64:79]
	v_and_b32_e32 v13, 0xffff0000, v14
	v_mul_f32_e64 v56, v56, s8
	v_mul_f32_e64 v57, v57, s8
	v_mul_f32_e64 v54, v54, s8
	v_mul_f32_e64 v55, v55, s8
	v_pk_mul_f32 v[60:61], v[60:61], s[8:9] op_sel_hi:[1,0]
	v_pk_mul_f32 v[40:41], v[40:41], s[8:9] op_sel_hi:[1,0]
	v_pk_mul_f32 v[42:43], v[42:43], s[8:9] op_sel_hi:[1,0]
	v_pk_mul_f32 v[36:37], v[36:37], s[8:9] op_sel_hi:[1,0]
	v_pk_mul_f32 v[38:39], v[38:39], s[8:9] op_sel_hi:[1,0]
	v_writelane_b32 v254, s0, 39
	v_cvt_pk_bf16_f32 v140, v40, v41
	v_cvt_pk_bf16_f32 v142, v42, v43
	v_pk_mul_f32 v[20:21], v[12:13], s[8:9] op_sel_hi:[1,0]
	v_lshlrev_b32_e32 v12, 16, v15
	v_and_b32_e32 v13, 0xffff0000, v15
	v_pk_mul_f32 v[22:23], v[12:13], s[8:9] op_sel_hi:[1,0]
	ds_read_b128 v[12:15], v207 offset:64
	s_waitcnt lgkmcnt(1)
; #define LAS __attribute__((address_space(3)))
; __device__ __forceinline__ f32x4 zero4v() { f32x4 z = (f32x4){0.f, 0.f, 0.f, 0.f}; asm volatile("" : "+v"(z)); return z; }
; #define MFMA32(a, b, c) __builtin_amdgcn_mfma_f32_32x32x16_bf16(a, b, c, 0, 0, 0)
; __device__ __forceinline__ void mla_unit(const Frame& F, int h, int q0, int key0, int ntiles, int mode, int su) {
;     ...
;     f32x16 O[4];
; #pragma unroll
;     for (int dt = 0; dt < 4; ++dt) { const f32x4 z = zero4v();
; #pragma unroll
;         for (int r = 0; r < 16; ++r) O[dt][r] = z[r & 3]; }
;     ...
;     {   const LAS unsigned char* kb = F.lds + MA_K_OFF + krd;
; #pragma unroll
;         for (int kt = 0; kt < 2; ++kt) { { const float nm = -m;
; #pragma unroll
;             for (int r = 0; r < 16; ++r) sA[kt][r] = nm; }
; #pragma unroll
;             for (int ks = 0; ks < 12; ++ks) { const bf16x8 kf = *(const LAS bf16x8*)(kb + kt * 32 * MA_KSTR + ks * 32); sA[kt] = MFMA32(kf, Qf[ks], sA[kt]); } } }
	v_mfma_f32_32x32x16_bf16 v[80:95], v[24:27], v[140:143], v[80:95]
	v_cvt_pk_bf16_f32 v144, v36, v37
	v_cvt_pk_bf16_f32 v146, v38, v39
	v_cvt_pk_bf16_f32 v158, v20, v21
	v_cvt_pk_bf16_f32 v159, v22, v23
	ds_read_b128 v[20:23], v207 offset:96
	v_lshlrev_b32_e32 v24, 16, v8
	v_and_b32_e32 v25, 0xffff0000, v8
	s_waitcnt lgkmcnt(1)
	v_mfma_f32_32x32x16_bf16 v[80:95], v[12:15], v[144:147], v[80:95]
	ds_read_b128 v[12:15], v207 offset:128
	v_lshlrev_b32_e32 v8, 16, v9
	v_and_b32_e32 v9, 0xffff0000, v9
	v_mul_f32_e64 v8, v8, s8
	v_mul_f32_e64 v9, v9, s8
	v_lshlrev_b32_e32 v26, 16, v10
	v_and_b32_e32 v27, 0xffff0000, v10
	v_lshlrev_b32_e32 v10, 16, v11
	s_waitcnt lgkmcnt(1)
	v_mfma_f32_32x32x16_bf16 v[80:95], v[20:23], v[148:151], v[80:95]
	v_and_b32_e32 v11, 0xffff0000, v11
	v_mul_f32_e64 v22, v10, s8
	v_mul_f32_e64 v23, v11, s8
	v_cvt_pk_bf16_f32 v161, v8, v9
	ds_read_b128 v[8:11], v207 offset:160
	v_pk_mul_f32 v[20:21], v[26:27], s[8:9] op_sel_hi:[1,0]
	v_cvt_pk_bf16_f32 v156, v28, v29
	v_cvt_pk_bf16_f32 v157, v30, v31
	s_waitcnt lgkmcnt(1)
	v_mfma_f32_32x32x16_bf16 v[80:95], v[12:15], v[152:155], v[80:95]
	v_lshlrev_b32_e32 v12, 16, v4
	v_and_b32_e32 v13, 0xffff0000, v4
	v_cvt_pk_bf16_f32 v162, v20, v21
	v_mul_f32_e64 v20, v12, s8
	v_mul_f32_e64 v21, v13, s8
	ds_read_b128 v[12:15], v207 offset:192
	v_pk_mul_f32 v[24:25], v[24:25], s[8:9] op_sel_hi:[1,0]
	v_cvt_pk_bf16_f32 v163, v22, v23
	s_waitcnt lgkmcnt(1)
	v_mfma_f32_32x32x16_bf16 v[80:95], v[8:11], v[156:159], v[80:95]
	v_lshlrev_b32_e32 v8, 16, v6
	v_and_b32_e32 v9, 0xffff0000, v6
	v_cvt_pk_bf16_f32 v160, v24, v25
	v_mul_f32_e64 v22, v8, s8
	v_mul_f32_e64 v23, v9, s8
	ds_read_b128 v[8:11], v207 offset:224
	v_lshlrev_b32_e32 v4, 16, v5
	v_and_b32_e32 v5, 0xffff0000, v5
	s_waitcnt lgkmcnt(1)
	v_mfma_f32_32x32x16_bf16 v[80:95], v[12:15], v[160:163], v[80:95]
	v_lshlrev_b32_e32 v6, 16, v7
	v_and_b32_e32 v7, 0xffff0000, v7
	v_mul_f32_e64 v4, v4, s8
	v_mul_f32_e64 v5, v5, s8
	v_mul_f32_e64 v6, v6, s8
	v_mul_f32_e64 v7, v7, s8
	v_cvt_pk_bf16_f32 v164, v20, v21
	v_cvt_pk_bf16_f32 v165, v4, v5
	v_cvt_pk_bf16_f32 v166, v22, v23
	v_cvt_pk_bf16_f32 v167, v6, v7
	ds_read_b128 v[4:7], v207 offset:256
	v_cvt_pk_bf16_f32 v169, v60, v61
	s_waitcnt lgkmcnt(1)
	v_mfma_f32_32x32x16_bf16 v[80:95], v[8:11], v[164:167], v[80:95]
	v_mul_f32_e64 v8, v44, s8
	v_mul_f32_e64 v9, v45, s8
	v_mul_f32_e32 v10, 0x3dd53b94, v53
	v_cvt_pk_bf16_f32 v168, v8, v9
	v_cvt_pk_bf16_f32 v170, v114, v115
	v_cvt_pk_bf16_f32 v171, v52, v10
	ds_read_b128 v[8:11], v207 offset:288
	v_cvt_pk_bf16_f32 v173, v54, v55
	s_waitcnt lgkmcnt(1)
	v_mfma_f32_32x32x16_bf16 v[80:95], v[4:7], v[168:171], v[80:95]
	v_mul_f32_e64 v4, v58, s8
	v_mul_f32_e64 v5, v59, s8
	v_mul_f32_e32 v6, 0x3dd53b94, v47
	v_cvt_pk_bf16_f32 v172, v4, v5
	v_cvt_pk_bf16_f32 v174, v56, v57
	v_cvt_pk_bf16_f32 v175, v62, v6
	ds_read_b128 v[4:7], v207 offset:320
	v_cvt_pk_bf16_f32 v177, v112, v113
	s_waitcnt lgkmcnt(1)
	v_mfma_f32_32x32x16_bf16 v[80:95], v[8:11], v[172:175], v[80:95]
	v_mul_f32_e64 v8, v98, s8
	v_mul_f32_e64 v9, v99, s8
	v_mul_f32_e32 v10, 0x3dd53b94, v63
	v_cvt_pk_bf16_f32 v176, v8, v9
	v_cvt_pk_bf16_f32 v178, v110, v111
	v_cvt_pk_bf16_f32 v179, v102, v10
	ds_read_b128 v[8:11], v207 offset:352
	v_mul_f32_e32 v12, 0x3dd53b94, v101
	s_waitcnt lgkmcnt(1)
	v_mfma_f32_32x32x16_bf16 v[80:95], v[4:7], v[176:179], v[80:95]
	v_mul_f32_e64 v4, v96, s8
	v_mul_f32_e64 v5, v97, s8
	v_mul_f32_e64 v6, v104, s8
	v_mul_f32_e64 v7, v105, s8
	v_cvt_pk_bf16_f32 v181, v4, v5
	v_cvt_pk_bf16_f32 v180, v6, v7
	v_cvt_pk_bf16_f32 v182, v108, v109
	v_cvt_pk_bf16_f32 v183, v106, v12
	v_writelane_b32 v254, s1, 40
	v_writelane_b32 v254, s2, 41
	s_waitcnt lgkmcnt(0)
	v_mfma_f32_32x32x16_bf16 v[80:95], v[8:11], v[180:183], v[80:95]
	ds_read_b128 v[4:7], v207 offset:12800
	ds_read_b128 v[8:11], v207 offset:12832
	v_writelane_b32 v254, s3, 42
	v_writelane_b32 v254, s4, 43
	v_writelane_b32 v254, s5, 44
	v_writelane_b32 v254, s6, 45
	v_writelane_b32 v254, s7, 46
	v_writelane_b32 v254, s8, 47
	s_waitcnt lgkmcnt(1)
	v_mfma_f32_32x32x16_bf16 v[64:79], v[4:7], v[136:139], v[64:79]
	v_writelane_b32 v254, s9, 48
	v_writelane_b32 v254, s10, 49
	v_writelane_b32 v254, s11, 50
	v_writelane_b32 v254, s12, 51
	v_writelane_b32 v254, s13, 52
	v_writelane_b32 v254, s14, 53
	v_writelane_b32 v254, s15, 54
	s_waitcnt lgkmcnt(0)
	v_mfma_f32_32x32x16_bf16 v[64:79], v[8:11], v[140:143], v[64:79]
	ds_read_b128 v[4:7], v207 offset:12864
	ds_read_b128 v[8:11], v207 offset:12896
	ds_read_b128 v[96:99], v207 offset:13120
	ds_read_b128 v[100:103], v207 offset:13152
	s_movk_i32 s0, 0x140
	v_mov_b32_e32 v52, v48
	v_mov_b32_e32 v53, v49
	v_mov_b32_e32 v54, v50
	s_waitcnt lgkmcnt(3)
	v_mfma_f32_32x32x16_bf16 v[64:79], v[4:7], v[144:147], v[64:79]
	ds_read_b128 v[4:7], v207 offset:12928
	v_mov_b32_e32 v55, v51
	v_mov_b32_e32 v56, v48
	v_mov_b32_e32 v57, v49
	v_mov_b32_e32 v58, v50
	v_mov_b32_e32 v59, v51
	v_mov_b32_e32 v60, v48
	s_waitcnt lgkmcnt(3)
	v_mfma_f32_32x32x16_bf16 v[64:79], v[8:11], v[148:151], v[64:79]
	ds_read_b128 v[8:11], v207 offset:12960
	v_mov_b32_e32 v61, v49
	v_mov_b32_e32 v62, v50
	v_mov_b32_e32 v63, v51
	v_mov_b32_e32 v36, v32
	v_mov_b32_e32 v37, v33
	v_mov_b32_e32 v38, v34
	s_waitcnt lgkmcnt(1)
	v_mfma_f32_32x32x16_bf16 v[64:79], v[4:7], v[152:155], v[64:79]
	ds_read_b128 v[4:7], v207 offset:12992
	v_mov_b32_e32 v39, v35
	v_mov_b32_e32 v40, v32
	v_mov_b32_e32 v41, v33
	v_mov_b32_e32 v42, v34
	v_mov_b32_e32 v43, v35
	v_mov_b32_e32 v44, v32
	s_waitcnt lgkmcnt(1)
	v_mfma_f32_32x32x16_bf16 v[64:79], v[8:11], v[156:159], v[64:79]
	ds_read_b128 v[8:11], v207 offset:13024
	v_mov_b32_e32 v45, v33
	v_mov_b32_e32 v46, v34
	v_mov_b32_e32 v47, v35
	v_mov_b32_e32 v20, v16
	v_mov_b32_e32 v21, v17
	v_mov_b32_e32 v22, v18
	s_waitcnt lgkmcnt(1)
; #define LAS __attribute__((address_space(3)))
; #define MFMA32(a, b, c) __builtin_amdgcn_mfma_f32_32x32x16_bf16(a, b, c, 0, 0, 0)
; __device__ __forceinline__ void mla_unit(const Frame& F, int h, int q0, int key0, int ntiles, int mode, int su) {
;     ...
;     const int krd = ql * MA_KSTR + 16 * hh;
;     const int vrd = (4 * hh + ((F.lane & 15) >> 2)) * MA_VSTR + (((F.lane >> 4) & 1) * 16 + (F.lane & 3) * 4) * 2;
;     f32x16 sA[2], sB[2];
;     {   const LAS unsigned char* kb = F.lds + MA_K_OFF + krd;
; #pragma unroll
;         for (int kt = 0; kt < 2; ++kt) { { const float nm = -m;
; #pragma unroll
;             for (int r = 0; r < 16; ++r) sA[kt][r] = nm; }
; #pragma unroll
;             for (int ks = 0; ks < 12; ++ks) { const bf16x8 kf = *(const LAS bf16x8*)(kb + kt * 32 * MA_KSTR + ks * 32); sA[kt] = MFMA32(kf, Qf[ks], sA[kt]); } } }
;     int c0 = 0, c1 = 1, c2 = 2;
;     static_assert(((SEQ + CTXL) / 64) % 2 == 0, "tile loop is unrolled by two");
	v_mfma_f32_32x32x16_bf16 v[64:79], v[4:7], v[160:163], v[64:79]
	ds_read_b128 v[4:7], v207 offset:13056
	v_mov_b32_e32 v23, v19
	v_mov_b32_e32 v24, v16
	v_mov_b32_e32 v25, v17
	v_mov_b32_e32 v26, v18
	v_mov_b32_e32 v27, v19
	v_mov_b32_e32 v28, v16
	s_waitcnt lgkmcnt(1)
	v_mfma_f32_32x32x16_bf16 v[64:79], v[8:11], v[164:167], v[64:79]
	ds_read_b128 v[10:13], v207 offset:13088
	v_mov_b32_e32 v29, v17
	v_mov_b32_e32 v30, v18
	v_mov_b32_e32 v31, v19
	v_mov_b32_e32 v8, v0
	v_mov_b32_e32 v9, v1
	v_mov_b32_e32 v14, v2
	s_waitcnt lgkmcnt(1)
	v_mfma_f32_32x32x16_bf16 v[64:79], v[4:7], v[168:171], v[64:79]
	v_mov_b32_e32 v4, v0
	v_mov_b32_e32 v5, v1
	v_mov_b32_e32 v6, v2
	v_mov_b32_e32 v7, v3
	v_mov_b32_e32 v15, v3
	s_mov_b32 s16, 2
	s_mov_b32 s17, 1
	s_waitcnt lgkmcnt(0)
	v_mfma_f32_32x32x16_bf16 v[64:79], v[10:13], v[172:175], v[64:79]
	v_mov_b32_e32 v10, v2
	v_mov_b32_e32 v11, v3
	v_mov_b32_e32 v12, v0
	v_mov_b32_e32 v13, v1
	v_mov_b32_e32 v208, 0
	v_mov_b32_e32 v211, 0
	s_mov_b32 s20, 0
	v_mfma_f32_32x32x16_bf16 v[64:79], v[96:99], v[176:179], v[64:79]
	v_lshlrev_b32_e32 v96, 2, v116
	v_lshrrev_b32_e32 v97, 2, v198
	v_and_or_b32 v96, v97, 3, v96
	v_and_b32_e32 v97, 16, v198
	v_lshlrev_b32_e32 v98, 2, v198
	v_and_or_b32 v97, v98, 12, v97
	v_mul_lo_u32 v96, v96, s0
	v_mfma_f32_32x32x16_bf16 v[64:79], v[100:103], v[180:183], v[64:79]
	v_lshl_or_b32 v209, v97, 1, v96
	s_add_i32 s0, 0, 0x12c00
	v_add_u32_e32 v210, s0, v209
	s_mov_b32 s0, 0
	v_readlane_b32 s24, v253, 22
	v_readlane_b32 s25, v253, 23
	v_readlane_b32 s26, v253, 24
	v_readlane_b32 s27, v253, 25
	s_nop 4
	s_mul_i32 s40, s17, 0x6400
	v_add_u32_e32 v212, s40, v207
	ds_read_b128 v[244:247], v212
	ds_read_b128 v[248:251], v212 offset:32
	ds_read_b128 v[230:233], v212 offset:64
.LBB0_724:
	s_add_i32 s19, s20, 2
	s_min_u32 s1, s19, 0x41
	s_mul_i32 s8, s16, 0x6400
	s_mov_b32 s18, s17
	s_mov_b32 s17, s0
	s_mul_i32 s0, s1, 0x30000
	s_and_b64 vcc, exec, s[4:5]
	s_add_i32 s21, s8, 0
	s_cbranch_vccnz .LBB0_726
	s_add_i32 m0, s21, 0x6000
	s_nop 4
	buffer_load_dwordx4 v201, s[24:27], s0 offen lds
.LBB0_726:
	s_lshl_b32 s22, s1, 17
	s_mul_i32 s1, s16, 0x5000
	s_add_i32 s23, s1, 0
	s_and_b64 vcc, exec, s[6:7]
	s_add_i32 s23, s23, 0x12c00
	s_cbranch_vccnz .LBB0_728
	s_add_i32 s1, s23, s11
	s_add_i32 m0, s1, 0x4000
	s_mov_b32 s14, s26
	s_mov_b32 s15, s27
	buffer_load_dwordx4 v205, s[12:15], s22 offen lds
.LBB0_728:
	s_mul_i32 s1, s18, 0x6400
	s_cmp_eq_u32 s20, 0
	s_cselect_b64 s[8:9], -1, 0
	s_add_i32 s1, s21, s10
	s_mov_b32 m0, s1
	v_xor_b32_e32 v96, 0x80000000, v208
	v_mov_b32_e32 v97, v96
	buffer_load_dwordx4 v129, s[24:27], s0 offen lds
	v_mov_b32_e32 v98, v96
	v_mov_b32_e32 v99, v96
	v_mov_b32_e32 v100, v96
	v_mov_b32_e32 v101, v96
	v_mov_b32_e32 v102, v96
	v_mov_b32_e32 v103, v96
	v_mov_b32_e32 v104, v96
	v_mov_b32_e32 v105, v96
	v_mov_b32_e32 v106, v96
	v_mov_b32_e32 v107, v96
	v_mov_b32_e32 v108, v96
	v_mov_b32_e32 v109, v96
	v_mov_b32_e32 v110, v96
	v_mov_b32_e32 v111, v96
	v_max_f32_e32 v130, v81, v81
	s_waitcnt lgkmcnt(2)
	v_mfma_f32_32x32x16_bf16 v[112:127], v[244:247], v[136:139], v[96:111]
	v_max_f32_e32 v184, v80, v80
	v_max_f32_e32 v130, v184, v130
	v_max3_f32 v130, v130, v82, v83
	v_max3_f32 v130, v130, v84, v85
	v_max3_f32 v130, v130, v86, v87
	s_add_i32 m0, s1, 0x2000
	ds_read_b128 v[184:187], v212 offset:96
	buffer_load_dwordx4 v131, s[24:27], s0 offen lds
	s_waitcnt lgkmcnt(2)
	v_mfma_f32_32x32x16_bf16 v[112:127], v[248:251], v[140:143], v[112:127]
	v_max3_f32 v130, v130, v88, v89
	v_max3_f32 v130, v130, v90, v91
	v_max3_f32 v130, v130, v92, v93
	v_max3_f32 v130, v130, v94, v95
	s_add_i32 m0, s1, 0x4000
	ds_read_b128 v[234:237], v212 offset:128
	buffer_load_dwordx4 v199, s[24:27], s0 offen lds
	s_waitcnt lgkmcnt(2)
	v_mfma_f32_32x32x16_bf16 v[112:127], v[230:233], v[144:147], v[112:127]
	v_max3_f32 v130, v130, v64, v65
	v_max3_f32 v130, v130, v66, v67
	v_max3_f32 v130, v130, v68, v69
	v_max3_f32 v130, v130, v70, v71
	s_add_i32 s23, s23, s10
	s_mov_b32 s14, s26
	s_mov_b32 s15, s27
	s_mov_b32 m0, s23
	ds_read_b128 v[188:191], v212 offset:160
	buffer_load_dwordx4 v203, s[12:15], s22 offen lds
	s_waitcnt lgkmcnt(2)
	v_mfma_f32_32x32x16_bf16 v[112:127], v[184:187], v[148:151], v[112:127]
	v_max3_f32 v130, v130, v72, v73
	v_max3_f32 v130, v130, v74, v75
	v_max3_f32 v130, v130, v76, v77
	v_max3_f32 v130, v130, v78, v79
	v_mov_b32_e32 v192, v130
	s_waitcnt lgkmcnt(1)
	v_mfma_f32_32x32x16_bf16 v[112:127], v[234:237], v[152:155], v[112:127]
	v_permlane32_swap_b32_e32 v130, v192
	v_max_f32_e32 v192, v192, v192
	v_max_f32_e32 v130, v130, v130
	v_max_f32_e32 v130, v130, v192
	ds_read_b128 v[184:187], v212 offset:192
	v_cmp_lt_f32_e32 vcc, s68, v130
	s_cmp_lg_u64 vcc, 0
	s_cselect_b64 s[0:1], -1, 0
	s_or_b64 s[0:1], s[8:9], s[0:1]
	s_and_b64 vcc, exec, s[0:1]
	s_cbranch_vccz .LBB0_730
	v_max_f32_e32 v192, v130, v130
	v_max_f32_e32 v192, 0, v192
	v_cndmask_b32_e64 v130, v192, v130, s[8:9]
	v_exp_f32_e64 v192, -v130
	v_add_f32_e32 v208, v208, v130
	v_pk_add_f32 v[80:81], v[80:81], v[130:131] op_sel_hi:[1,0] neg_lo:[0,1] neg_hi:[0,1]
	v_pk_add_f32 v[82:83], v[82:83], v[130:131] op_sel_hi:[1,0] neg_lo:[0,1] neg_hi:[0,1]
	v_cndmask_b32_e64 v202, v192, 1.0, s[8:9]
	v_pk_add_f32 v[84:85], v[84:85], v[130:131] op_sel_hi:[1,0] neg_lo:[0,1] neg_hi:[0,1]
	v_pk_add_f32 v[86:87], v[86:87], v[130:131] op_sel_hi:[1,0] neg_lo:[0,1] neg_hi:[0,1]
	v_pk_add_f32 v[88:89], v[88:89], v[130:131] op_sel_hi:[1,0] neg_lo:[0,1] neg_hi:[0,1]
	v_pk_add_f32 v[90:91], v[90:91], v[130:131] op_sel_hi:[1,0] neg_lo:[0,1] neg_hi:[0,1]
	v_pk_add_f32 v[92:93], v[92:93], v[130:131] op_sel_hi:[1,0] neg_lo:[0,1] neg_hi:[0,1]
	v_pk_add_f32 v[94:95], v[94:95], v[130:131] op_sel_hi:[1,0] neg_lo:[0,1] neg_hi:[0,1]
	v_pk_add_f32 v[64:65], v[64:65], v[130:131] op_sel_hi:[1,0] neg_lo:[0,1] neg_hi:[0,1]
	v_pk_add_f32 v[66:67], v[66:67], v[130:131] op_sel_hi:[1,0] neg_lo:[0,1] neg_hi:[0,1]
	v_pk_add_f32 v[68:69], v[68:69], v[130:131] op_sel_hi:[1,0] neg_lo:[0,1] neg_hi:[0,1]
	v_pk_add_f32 v[70:71], v[70:71], v[130:131] op_sel_hi:[1,0] neg_lo:[0,1] neg_hi:[0,1]
	v_pk_add_f32 v[72:73], v[72:73], v[130:131] op_sel_hi:[1,0] neg_lo:[0,1] neg_hi:[0,1]
	v_pk_add_f32 v[74:75], v[74:75], v[130:131] op_sel_hi:[1,0] neg_lo:[0,1] neg_hi:[0,1]
	v_pk_add_f32 v[76:77], v[76:77], v[130:131] op_sel_hi:[1,0] neg_lo:[0,1] neg_hi:[0,1]
	v_pk_add_f32 v[78:79], v[78:79], v[130:131] op_sel_hi:[1,0] neg_lo:[0,1] neg_hi:[0,1]
	v_mul_f32_e32 v211, v211, v202
	s_branch .LBB0_731

.LBB0_731:
	s_add_i32 m0, s23, 0x2000
	s_mov_b32 s14, s26
	s_mov_b32 s15, s27
	ds_read_b128 v[230:233], v212 offset:224
	buffer_load_dwordx4 v204, s[12:15], s22 offen lds
	s_waitcnt lgkmcnt(2)
	v_mfma_f32_32x32x16_bf16 v[112:127], v[188:191], v[156:159], v[112:127]
	v_exp_f32_e32 v80, v80
	v_exp_f32_e32 v81, v81
	s_nop 0
	v_add_f32_e32 v188, v81, v80
	v_add_f32_e32 v192, 0, v188
	s_waitcnt lgkmcnt(1)
	v_mfma_f32_32x32x16_bf16 v[112:127], v[184:187], v[160:163], v[112:127]
	v_exp_f32_e32 v82, v82
	v_exp_f32_e32 v184, v83
	ds_read_b128 v[188:191], v212 offset:256
	v_add_f32_e32 v83, v184, v82
	v_add_f32_e32 v83, v83, v192
	s_waitcnt lgkmcnt(1)
	v_mfma_f32_32x32x16_bf16 v[112:127], v[230:233], v[164:167], v[112:127]
	v_exp_f32_e32 v185, v84
	v_exp_f32_e32 v186, v85
	ds_read_b128 v[234:237], v212 offset:288
	v_add_f32_e32 v84, v186, v185
	v_add_f32_e32 v83, v84, v83
	s_waitcnt lgkmcnt(1)
	v_mfma_f32_32x32x16_bf16 v[112:127], v[188:191], v[168:171], v[112:127]
	v_exp_f32_e32 v187, v86
	v_exp_f32_e32 v188, v87
	ds_read_b128 v[230:233], v212 offset:320
	v_add_f32_e32 v84, v188, v187
	v_add_f32_e32 v85, v84, v83
	s_waitcnt lgkmcnt(1)
	v_mfma_f32_32x32x16_bf16 v[112:127], v[234:237], v[172:175], v[112:127]
	v_exp_f32_e32 v83, v88
	v_exp_f32_e32 v84, v89
	ds_read_b128 v[238:241], v212 offset:352
	v_add_f32_e32 v86, v84, v83
	v_add_f32_e32 v87, v86, v85
	s_waitcnt lgkmcnt(1)
	v_mfma_f32_32x32x16_bf16 v[112:127], v[230:233], v[176:179], v[112:127]
	v_exp_f32_e32 v85, v90
	v_exp_f32_e32 v86, v91
	ds_read_b128 v[234:237], v212 offset:12800
	v_add_f32_e32 v88, v86, v85
	v_add_f32_e32 v89, v88, v87
	s_waitcnt lgkmcnt(1)
	v_mfma_f32_32x32x16_bf16 v[112:127], v[238:241], v[180:183], v[112:127]
	v_exp_f32_e32 v87, v92
	v_exp_f32_e32 v88, v93
	ds_read_b128 v[230:233], v212 offset:12832
	v_add_f32_e32 v90, v88, v87
	v_add_f32_e32 v89, v90, v89
	s_waitcnt lgkmcnt(1)
	v_mfma_f32_32x32x16_bf16 v[96:111], v[234:237], v[136:139], v[96:111]
	v_exp_f32_e32 v91, v94
	v_exp_f32_e32 v92, v95
	ds_read_b128 v[238:241], v212 offset:12864
	v_add_f32_e32 v90, v92, v91
	v_add_f32_e32 v89, v90, v89
	s_waitcnt lgkmcnt(1)
	v_mfma_f32_32x32x16_bf16 v[96:111], v[230:233], v[140:143], v[96:111]
	v_exp_f32_e32 v64, v64
	v_exp_f32_e32 v65, v65
	ds_read_b128 v[234:237], v212 offset:12896
	v_add_f32_e32 v90, v65, v64
	v_add_f32_e32 v89, v90, v89
	s_waitcnt lgkmcnt(1)
	v_mfma_f32_32x32x16_bf16 v[96:111], v[238:241], v[144:147], v[96:111]
	v_exp_f32_e32 v66, v66
	v_exp_f32_e32 v67, v67
	ds_read_b128 v[230:233], v212 offset:12928
	v_add_f32_e32 v90, v67, v66
	v_add_f32_e32 v93, v90, v89
	s_waitcnt lgkmcnt(1)
	v_mfma_f32_32x32x16_bf16 v[96:111], v[234:237], v[148:151], v[96:111]
	v_exp_f32_e32 v89, v68
	v_exp_f32_e32 v90, v69
	ds_read_b128 v[238:241], v212 offset:12960
	v_add_f32_e32 v68, v90, v89
	v_add_f32_e32 v68, v68, v93
	s_waitcnt lgkmcnt(1)
	v_mfma_f32_32x32x16_bf16 v[96:111], v[230:233], v[152:155], v[96:111]
	v_exp_f32_e32 v93, v70
	v_exp_f32_e32 v94, v71
	ds_read_b128 v[234:237], v212 offset:12992
	v_add_f32_e32 v69, v94, v93
	v_add_f32_e32 v70, v69, v68
	s_waitcnt lgkmcnt(1)
	v_mfma_f32_32x32x16_bf16 v[96:111], v[238:241], v[156:159], v[96:111]
	v_exp_f32_e32 v68, v72
	v_exp_f32_e32 v69, v73
	ds_read_b128 v[230:233], v212 offset:13024
	v_add_f32_e32 v71, v69, v68
	v_add_f32_e32 v72, v71, v70
	s_waitcnt lgkmcnt(1)
	v_mfma_f32_32x32x16_bf16 v[96:111], v[234:237], v[160:163], v[96:111]
	v_exp_f32_e32 v70, v74
	v_exp_f32_e32 v71, v75
	ds_read_b128 v[238:241], v212 offset:13056
	v_add_f32_e32 v73, v71, v70
	v_add_f32_e32 v74, v73, v72
	s_waitcnt lgkmcnt(1)
	v_mfma_f32_32x32x16_bf16 v[96:111], v[230:233], v[164:167], v[96:111]
	v_exp_f32_e32 v72, v76
	v_exp_f32_e32 v73, v77
	ds_read_b128 v[234:237], v212 offset:13088
	v_add_f32_e32 v75, v73, v72
	v_add_f32_e32 v95, v75, v74
	s_waitcnt lgkmcnt(1)
	v_mfma_f32_32x32x16_bf16 v[96:111], v[238:241], v[168:171], v[96:111]
	v_exp_f32_e32 v74, v78
	v_exp_f32_e32 v75, v79
	ds_read_b128 v[76:79], v212 offset:13120
	v_add_f32_e32 v189, v75, v74
	v_add_f32_e32 v95, v189, v95
	s_waitcnt lgkmcnt(1)
	v_mfma_f32_32x32x16_bf16 v[96:111], v[234:237], v[172:175], v[96:111]
	ds_read_b128 v[230:233], v212 offset:13152
	v_add_f32_e32 v211, v211, v95
	s_waitcnt lgkmcnt(1)
	v_mfma_f32_32x32x16_bf16 v[96:111], v[76:79], v[176:179], v[96:111]
	s_waitcnt lgkmcnt(0)
	v_mfma_f32_32x32x16_bf16 v[96:111], v[230:233], v[180:183], v[96:111]
	s_and_b64 vcc, exec, s[0:1]
	s_cbranch_vccz .LBB0_733
	v_pk_mul_f32 v[62:63], v[62:63], v[202:203] op_sel_hi:[1,0]
	v_pk_mul_f32 v[60:61], v[60:61], v[202:203] op_sel_hi:[1,0]
	v_pk_mul_f32 v[58:59], v[58:59], v[202:203] op_sel_hi:[1,0]
	v_pk_mul_f32 v[56:57], v[56:57], v[202:203] op_sel_hi:[1,0]
	v_pk_mul_f32 v[54:55], v[54:55], v[202:203] op_sel_hi:[1,0]
	v_pk_mul_f32 v[52:53], v[52:53], v[202:203] op_sel_hi:[1,0]
	v_pk_mul_f32 v[50:51], v[50:51], v[202:203] op_sel_hi:[1,0]
	v_pk_mul_f32 v[48:49], v[48:49], v[202:203] op_sel_hi:[1,0]
	v_pk_mul_f32 v[46:47], v[46:47], v[202:203] op_sel_hi:[1,0]
	v_pk_mul_f32 v[44:45], v[44:45], v[202:203] op_sel_hi:[1,0]
	v_pk_mul_f32 v[42:43], v[42:43], v[202:203] op_sel_hi:[1,0]
	v_pk_mul_f32 v[40:41], v[40:41], v[202:203] op_sel_hi:[1,0]
	v_pk_mul_f32 v[38:39], v[38:39], v[202:203] op_sel_hi:[1,0]
	v_pk_mul_f32 v[36:37], v[36:37], v[202:203] op_sel_hi:[1,0]
	v_pk_mul_f32 v[34:35], v[34:35], v[202:203] op_sel_hi:[1,0]
	v_pk_mul_f32 v[32:33], v[32:33], v[202:203] op_sel_hi:[1,0]
	v_pk_mul_f32 v[30:31], v[30:31], v[202:203] op_sel_hi:[1,0]
	v_pk_mul_f32 v[28:29], v[28:29], v[202:203] op_sel_hi:[1,0]
	v_pk_mul_f32 v[26:27], v[26:27], v[202:203] op_sel_hi:[1,0]
	v_pk_mul_f32 v[24:25], v[24:25], v[202:203] op_sel_hi:[1,0]
	v_pk_mul_f32 v[22:23], v[22:23], v[202:203] op_sel_hi:[1,0]
	v_pk_mul_f32 v[20:21], v[20:21], v[202:203] op_sel_hi:[1,0]
	v_pk_mul_f32 v[18:19], v[18:19], v[202:203] op_sel_hi:[1,0]
	v_pk_mul_f32 v[16:17], v[16:17], v[202:203] op_sel_hi:[1,0]
	v_pk_mul_f32 v[14:15], v[14:15], v[202:203] op_sel_hi:[1,0]
	v_pk_mul_f32 v[12:13], v[12:13], v[202:203] op_sel_hi:[1,0]
	v_pk_mul_f32 v[10:11], v[10:11], v[202:203] op_sel_hi:[1,0]
	v_pk_mul_f32 v[8:9], v[8:9], v[202:203] op_sel_hi:[1,0]
	v_pk_mul_f32 v[6:7], v[6:7], v[202:203] op_sel_hi:[1,0]
	v_pk_mul_f32 v[4:5], v[4:5], v[202:203] op_sel_hi:[1,0]
	v_pk_mul_f32 v[2:3], v[2:3], v[202:203] op_sel_hi:[1,0]
	v_pk_mul_f32 v[0:1], v[0:1], v[202:203] op_sel_hi:[1,0]
	v_sub_f32_e32 v127, v127, v130
	v_sub_f32_e32 v126, v126, v130
	v_sub_f32_e32 v125, v125, v130
	v_sub_f32_e32 v124, v124, v130
	v_sub_f32_e32 v123, v123, v130
	v_sub_f32_e32 v122, v122, v130
	v_sub_f32_e32 v121, v121, v130
	v_sub_f32_e32 v120, v120, v130
	v_sub_f32_e32 v119, v119, v130
	v_sub_f32_e32 v118, v118, v130
	v_sub_f32_e32 v117, v117, v130
	v_sub_f32_e32 v116, v116, v130
	v_sub_f32_e32 v115, v115, v130
	v_sub_f32_e32 v114, v114, v130
	v_sub_f32_e32 v113, v113, v130
	v_sub_f32_e32 v112, v112, v130
	v_sub_f32_e32 v111, v111, v130
	v_sub_f32_e32 v110, v110, v130
	v_sub_f32_e32 v109, v109, v130
	v_sub_f32_e32 v108, v108, v130
	v_sub_f32_e32 v107, v107, v130
	v_sub_f32_e32 v106, v106, v130
	v_sub_f32_e32 v105, v105, v130
	v_sub_f32_e32 v104, v104, v130
	v_sub_f32_e32 v103, v103, v130
	v_sub_f32_e32 v102, v102, v130
	v_sub_f32_e32 v101, v101, v130
	v_sub_f32_e32 v100, v100, v130
	v_sub_f32_e32 v99, v99, v130
	v_sub_f32_e32 v98, v98, v130
	v_sub_f32_e32 v97, v97, v130
	v_sub_f32_e32 v96, v96, v130
.LBB0_733:
	s_mul_i32 s0, s17, 0x5000
	s_add_i32 s0, s0, 0
	s_add_i32 s0, s0, 0x12c00
	v_add_u32_e32 v95, s0, v209
	ds_read_b64_tr_b16 v[76:77], v95
	ds_read_b64_tr_b16 v[78:79], v95 offset:2560
	v_cvt_pk_bf16_f32 v230, v80, v81
	v_cvt_pk_bf16_f32 v231, v82, v184
	v_cvt_pk_bf16_f32 v232, v185, v186
	v_cvt_pk_bf16_f32 v233, v187, v188
	ds_read_b64_tr_b16 v[184:185], v95 offset:128
	ds_read_b64_tr_b16 v[186:187], v95 offset:2688
	ds_read_b64_tr_b16 v[188:189], v95 offset:192
	ds_read_b64_tr_b16 v[190:191], v95 offset:2752
	ds_read_b64_tr_b16 v[220:221], v95 offset:64
	ds_read_b64_tr_b16 v[222:223], v95 offset:2624
	s_waitcnt lgkmcnt(6)
	v_mfma_f32_32x32x16_bf16 v[48:63], v[76:79], v[230:233], v[48:63]
	ds_read_b64_tr_b16 v[244:245], v95 offset:5120
	ds_read_b64_tr_b16 v[246:247], v95 offset:7680
	v_cvt_pk_bf16_f32 v80, v83, v84
	v_cvt_pk_bf16_f32 v81, v85, v86
	v_cvt_pk_bf16_f32 v82, v87, v88
	v_cvt_pk_bf16_f32 v83, v91, v92
	v_cvt_pk_bf16_f32 v64, v64, v65
	v_cvt_pk_bf16_f32 v65, v66, v67
	s_waitcnt lgkmcnt(6)
	v_mfma_f32_32x32x16_bf16 v[16:31], v[184:187], v[230:233], v[16:31]
	ds_read_b64_tr_b16 v[248:249], v95 offset:5184
	ds_read_b64_tr_b16 v[250:251], v95 offset:7744
	v_cvt_pk_bf16_f32 v66, v89, v90
	v_cvt_pk_bf16_f32 v67, v93, v94
	v_cvt_pk_bf16_f32 v68, v68, v69
	v_cvt_pk_bf16_f32 v69, v70, v71
	v_cvt_pk_bf16_f32 v70, v72, v73
	v_cvt_pk_bf16_f32 v71, v74, v75
	s_waitcnt lgkmcnt(6)
	v_mfma_f32_32x32x16_bf16 v[0:15], v[188:191], v[230:233], v[0:15]
	ds_read_b64_tr_b16 v[76:77], v95 offset:5248
	ds_read_b64_tr_b16 v[78:79], v95 offset:7808
	s_min_u32 s8, s20, 62
	s_add_i32 s8, s8, 3
	s_mul_i32 s9, s17, 0x6400
	s_mul_i32 s1, s8, 0x30000
	s_add_i32 s9, s9, 0
	s_and_b64 vcc, exec, s[4:5]
	s_waitcnt lgkmcnt(6)
	v_mfma_f32_32x32x16_bf16 v[32:47], v[220:223], v[230:233], v[32:47]
	ds_read_b64_tr_b16 v[184:185], v95 offset:5312
	ds_read_b64_tr_b16 v[186:187], v95 offset:7872
	s_waitcnt lgkmcnt(6)
	v_mfma_f32_32x32x16_bf16 v[48:63], v[244:247], v[80:83], v[48:63]
	ds_read_b64_tr_b16 v[188:189], v95 offset:10240
	ds_read_b64_tr_b16 v[190:191], v95 offset:12800
	s_waitcnt lgkmcnt(6)
	v_mfma_f32_32x32x16_bf16 v[32:47], v[248:251], v[80:83], v[32:47]
	ds_read_b64_tr_b16 v[220:221], v95 offset:10304
	ds_read_b64_tr_b16 v[222:223], v95 offset:12864
	s_waitcnt lgkmcnt(6)
	v_mfma_f32_32x32x16_bf16 v[16:31], v[76:79], v[80:83], v[16:31]
	ds_read_b64_tr_b16 v[244:245], v95 offset:10368
	ds_read_b64_tr_b16 v[246:247], v95 offset:12928
	s_waitcnt lgkmcnt(6)
	v_mfma_f32_32x32x16_bf16 v[0:15], v[184:187], v[80:83], v[0:15]
	ds_read_b64_tr_b16 v[248:249], v95 offset:10432
	ds_read_b64_tr_b16 v[250:251], v95 offset:12992
	s_waitcnt lgkmcnt(6)
	v_mfma_f32_32x32x16_bf16 v[48:63], v[188:191], v[64:67], v[48:63]
	ds_read_b64_tr_b16 v[76:77], v95 offset:15360
	ds_read_b64_tr_b16 v[78:79], v95 offset:17920
	s_waitcnt lgkmcnt(6)
	v_mfma_f32_32x32x16_bf16 v[32:47], v[220:223], v[64:67], v[32:47]
	ds_read_b64_tr_b16 v[184:185], v95 offset:15424
	ds_read_b64_tr_b16 v[186:187], v95 offset:17984
	s_waitcnt lgkmcnt(6)
	v_mfma_f32_32x32x16_bf16 v[16:31], v[244:247], v[64:67], v[16:31]
	ds_read_b64_tr_b16 v[188:189], v95 offset:15488
	ds_read_b64_tr_b16 v[190:191], v95 offset:18048
	s_waitcnt lgkmcnt(6)
	v_mfma_f32_32x32x16_bf16 v[0:15], v[248:251], v[64:67], v[0:15]
	ds_read_b64_tr_b16 v[220:221], v95 offset:15552
	ds_read_b64_tr_b16 v[222:223], v95 offset:18112
	s_waitcnt lgkmcnt(6)
	v_mfma_f32_32x32x16_bf16 v[48:63], v[76:79], v[68:71], v[48:63]
	s_waitcnt lgkmcnt(4)
	v_mfma_f32_32x32x16_bf16 v[32:47], v[184:187], v[68:71], v[32:47]
	s_waitcnt vmcnt(0)
	s_waitcnt lgkmcnt(0)
	s_barrier
	v_add_u32_e32 v212, s21, v206
	ds_read_b128 v[244:247], v212
	ds_read_b128 v[248:251], v212 offset:32
	ds_read_b128 v[230:233], v212 offset:64
	v_mfma_f32_32x32x16_bf16 v[16:31], v[188:191], v[68:71], v[16:31]
	v_mfma_f32_32x32x16_bf16 v[0:15], v[220:223], v[68:71], v[0:15]
	s_cbranch_vccz .LBB0_738
	s_and_b64 vcc, exec, s[6:7]
	s_lshl_b32 s8, s8, 17
	s_cbranch_vccnz .LBB0_736
.LBB0_735:
	s_add_i32 s14, s0, s11
	s_add_i32 m0, s14, 0x4000
	s_mov_b32 s14, s26
	s_mov_b32 s15, s27
	buffer_load_dwordx4 v205, s[12:15], s8 offen lds
.LBB0_736:
	s_add_i32 s9, s9, s10
	s_mov_b32 m0, s9
	v_xor_b32_e32 v64, 0x80000000, v208
	v_mov_b32_e32 v65, v64
	buffer_load_dwordx4 v129, s[24:27], s1 offen lds
	v_mov_b32_e32 v66, v64
	v_mov_b32_e32 v67, v64
	v_mov_b32_e32 v68, v64
	v_mov_b32_e32 v69, v64
	v_mov_b32_e32 v70, v64
	v_mov_b32_e32 v71, v64
	v_mov_b32_e32 v72, v64
	v_mov_b32_e32 v73, v64
	v_mov_b32_e32 v74, v64
	v_mov_b32_e32 v75, v64
	v_mov_b32_e32 v76, v64
	v_mov_b32_e32 v77, v64
	v_mov_b32_e32 v78, v64
	v_mov_b32_e32 v79, v64
	v_max_f32_e32 v130, v113, v113
	s_waitcnt lgkmcnt(2)
	v_mfma_f32_32x32x16_bf16 v[80:95], v[244:247], v[136:139], v[64:79]
	v_max_f32_e32 v184, v112, v112
	v_max_f32_e32 v130, v184, v130
	v_max3_f32 v130, v130, v114, v115
	v_max3_f32 v130, v130, v116, v117
	v_max3_f32 v130, v130, v118, v119
	s_add_i32 m0, s9, 0x2000
	ds_read_b128 v[184:187], v212 offset:96
	buffer_load_dwordx4 v131, s[24:27], s1 offen lds
	s_waitcnt lgkmcnt(2)
	v_mfma_f32_32x32x16_bf16 v[80:95], v[248:251], v[140:143], v[80:95]
	v_max3_f32 v130, v130, v120, v121
	v_max3_f32 v130, v130, v122, v123
	v_max3_f32 v130, v130, v124, v125
	v_max3_f32 v130, v130, v126, v127
	s_add_i32 m0, s9, 0x4000
	ds_read_b128 v[234:237], v212 offset:128
	buffer_load_dwordx4 v199, s[24:27], s1 offen lds
	s_waitcnt lgkmcnt(2)
	v_mfma_f32_32x32x16_bf16 v[80:95], v[230:233], v[144:147], v[80:95]
	v_max3_f32 v130, v130, v96, v97
	v_max3_f32 v130, v130, v98, v99
	v_max3_f32 v130, v130, v100, v101
	v_max3_f32 v130, v130, v102, v103
	s_add_i32 s9, s0, s10
	s_mov_b32 s14, s26
	s_mov_b32 s15, s27
	s_mov_b32 m0, s9
	ds_read_b128 v[188:191], v212 offset:160
	buffer_load_dwordx4 v203, s[12:15], s8 offen lds
	s_waitcnt lgkmcnt(2)
	v_mfma_f32_32x32x16_bf16 v[80:95], v[184:187], v[148:151], v[80:95]
	v_max3_f32 v130, v130, v104, v105
	v_max3_f32 v130, v130, v106, v107
	v_max3_f32 v130, v130, v108, v109
	v_max3_f32 v130, v130, v110, v111
	s_waitcnt lgkmcnt(1)
	v_mfma_f32_32x32x16_bf16 v[80:95], v[234:237], v[152:155], v[80:95]
	v_mov_b32_e32 v192, v130
	s_nop 1
	v_permlane32_swap_b32_e32 v130, v192
	ds_read_b128 v[184:187], v212 offset:192
	v_max_f32_e32 v192, v192, v192
	v_max_f32_e32 v130, v130, v130
	v_max_f32_e32 v130, v130, v192
	v_cmp_lt_f32_e32 vcc, s68, v130
	s_cmp_lg_u64 vcc, 0
	s_cselect_b64 s[0:1], -1, 0
	s_cbranch_vccz .LBB0_739
	v_max_f32_e32 v130, v130, v130
	v_max_f32_e32 v130, 0, v130
	v_exp_f32_e64 v202, -v130
	v_add_f32_e32 v208, v208, v130
	v_pk_add_f32 v[112:113], v[112:113], v[130:131] op_sel_hi:[1,0] neg_lo:[0,1] neg_hi:[0,1]
	v_pk_add_f32 v[114:115], v[114:115], v[130:131] op_sel_hi:[1,0] neg_lo:[0,1] neg_hi:[0,1]
	v_pk_add_f32 v[116:117], v[116:117], v[130:131] op_sel_hi:[1,0] neg_lo:[0,1] neg_hi:[0,1]
	v_pk_add_f32 v[118:119], v[118:119], v[130:131] op_sel_hi:[1,0] neg_lo:[0,1] neg_hi:[0,1]
	v_pk_add_f32 v[120:121], v[120:121], v[130:131] op_sel_hi:[1,0] neg_lo:[0,1] neg_hi:[0,1]
	v_pk_add_f32 v[122:123], v[122:123], v[130:131] op_sel_hi:[1,0] neg_lo:[0,1] neg_hi:[0,1]
	v_pk_add_f32 v[124:125], v[124:125], v[130:131] op_sel_hi:[1,0] neg_lo:[0,1] neg_hi:[0,1]
	v_pk_add_f32 v[126:127], v[126:127], v[130:131] op_sel_hi:[1,0] neg_lo:[0,1] neg_hi:[0,1]
	v_pk_add_f32 v[96:97], v[96:97], v[130:131] op_sel_hi:[1,0] neg_lo:[0,1] neg_hi:[0,1]
	v_pk_add_f32 v[98:99], v[98:99], v[130:131] op_sel_hi:[1,0] neg_lo:[0,1] neg_hi:[0,1]
	v_pk_add_f32 v[100:101], v[100:101], v[130:131] op_sel_hi:[1,0] neg_lo:[0,1] neg_hi:[0,1]
	v_pk_add_f32 v[102:103], v[102:103], v[130:131] op_sel_hi:[1,0] neg_lo:[0,1] neg_hi:[0,1]
	v_pk_add_f32 v[104:105], v[104:105], v[130:131] op_sel_hi:[1,0] neg_lo:[0,1] neg_hi:[0,1]
	v_pk_add_f32 v[106:107], v[106:107], v[130:131] op_sel_hi:[1,0] neg_lo:[0,1] neg_hi:[0,1]
	v_pk_add_f32 v[108:109], v[108:109], v[130:131] op_sel_hi:[1,0] neg_lo:[0,1] neg_hi:[0,1]
	v_pk_add_f32 v[110:111], v[110:111], v[130:131] op_sel_hi:[1,0] neg_lo:[0,1] neg_hi:[0,1]
	v_mul_f32_e32 v211, v211, v202
	s_branch .LBB0_740
.LBB0_738:
	s_add_i32 m0, s9, 0x6000
	s_nop 4
	buffer_load_dwordx4 v201, s[24:27], s1 offen lds
	s_and_b64 vcc, exec, s[6:7]
	s_lshl_b32 s8, s8, 17
	s_cbranch_vccz .LBB0_735
	s_branch .LBB0_736

.LBB0_740:
	s_add_i32 m0, s9, 0x2000
	s_mov_b32 s14, s26
	s_mov_b32 s15, s27
	ds_read_b128 v[230:233], v212 offset:224
	buffer_load_dwordx4 v204, s[12:15], s8 offen lds
	s_waitcnt lgkmcnt(2)
	v_mfma_f32_32x32x16_bf16 v[80:95], v[188:191], v[156:159], v[80:95]
	v_exp_f32_e32 v112, v112
	v_exp_f32_e32 v113, v113
	s_nop 0
	v_add_f32_e32 v188, v113, v112
	v_add_f32_e32 v192, 0, v188
	s_waitcnt lgkmcnt(1)
	v_mfma_f32_32x32x16_bf16 v[80:95], v[184:187], v[160:163], v[80:95]
	v_exp_f32_e32 v114, v114
	v_exp_f32_e32 v184, v115
	ds_read_b128 v[188:191], v212 offset:256
	v_add_f32_e32 v115, v184, v114
	v_add_f32_e32 v115, v115, v192
	s_waitcnt lgkmcnt(1)
	v_mfma_f32_32x32x16_bf16 v[80:95], v[230:233], v[164:167], v[80:95]
	v_exp_f32_e32 v185, v116
	v_exp_f32_e32 v186, v117
	ds_read_b128 v[234:237], v212 offset:288
	v_add_f32_e32 v116, v186, v185
	v_add_f32_e32 v115, v116, v115
	s_waitcnt lgkmcnt(1)
	v_mfma_f32_32x32x16_bf16 v[80:95], v[188:191], v[168:171], v[80:95]
	v_exp_f32_e32 v187, v118
	v_exp_f32_e32 v188, v119
	ds_read_b128 v[230:233], v212 offset:320
	v_add_f32_e32 v116, v188, v187
	v_add_f32_e32 v117, v116, v115
	s_waitcnt lgkmcnt(1)
	v_mfma_f32_32x32x16_bf16 v[80:95], v[234:237], v[172:175], v[80:95]
	v_exp_f32_e32 v115, v120
	v_exp_f32_e32 v116, v121
	ds_read_b128 v[238:241], v212 offset:352
	v_add_f32_e32 v118, v116, v115
	v_add_f32_e32 v119, v118, v117
	s_waitcnt lgkmcnt(1)
	v_mfma_f32_32x32x16_bf16 v[80:95], v[230:233], v[176:179], v[80:95]
	v_exp_f32_e32 v117, v122
	v_exp_f32_e32 v118, v123
	ds_read_b128 v[234:237], v212 offset:12800
	v_add_f32_e32 v120, v118, v117
	v_add_f32_e32 v121, v120, v119
	s_waitcnt lgkmcnt(1)
	v_mfma_f32_32x32x16_bf16 v[80:95], v[238:241], v[180:183], v[80:95]
	v_exp_f32_e32 v119, v124
	v_exp_f32_e32 v120, v125
	ds_read_b128 v[230:233], v212 offset:12832
	v_add_f32_e32 v122, v120, v119
	v_add_f32_e32 v121, v122, v121
	s_waitcnt lgkmcnt(1)
	v_mfma_f32_32x32x16_bf16 v[64:79], v[234:237], v[136:139], v[64:79]
	v_exp_f32_e32 v123, v126
	v_exp_f32_e32 v124, v127
	ds_read_b128 v[238:241], v212 offset:12864
	v_add_f32_e32 v122, v124, v123
	v_add_f32_e32 v121, v122, v121
	s_waitcnt lgkmcnt(1)
	v_mfma_f32_32x32x16_bf16 v[64:79], v[230:233], v[140:143], v[64:79]
	v_exp_f32_e32 v96, v96
	v_exp_f32_e32 v97, v97
	ds_read_b128 v[234:237], v212 offset:12896
	v_add_f32_e32 v122, v97, v96
	v_add_f32_e32 v121, v122, v121
	s_waitcnt lgkmcnt(1)
	v_mfma_f32_32x32x16_bf16 v[64:79], v[238:241], v[144:147], v[64:79]
	v_exp_f32_e32 v98, v98
	v_exp_f32_e32 v99, v99
	ds_read_b128 v[230:233], v212 offset:12928
	v_add_f32_e32 v122, v99, v98
	v_add_f32_e32 v125, v122, v121
	s_waitcnt lgkmcnt(1)
	v_mfma_f32_32x32x16_bf16 v[64:79], v[234:237], v[148:151], v[64:79]
	v_exp_f32_e32 v121, v100
	v_exp_f32_e32 v122, v101
	ds_read_b128 v[238:241], v212 offset:12960
	v_add_f32_e32 v100, v122, v121
	v_add_f32_e32 v100, v100, v125
	s_waitcnt lgkmcnt(1)
	v_mfma_f32_32x32x16_bf16 v[64:79], v[230:233], v[152:155], v[64:79]
	v_exp_f32_e32 v125, v102
	v_exp_f32_e32 v126, v103
	ds_read_b128 v[234:237], v212 offset:12992
	v_add_f32_e32 v101, v126, v125
	v_add_f32_e32 v102, v101, v100
	s_waitcnt lgkmcnt(1)
	v_mfma_f32_32x32x16_bf16 v[64:79], v[238:241], v[156:159], v[64:79]
	v_exp_f32_e32 v100, v104
	v_exp_f32_e32 v101, v105
	ds_read_b128 v[230:233], v212 offset:13024
	v_add_f32_e32 v103, v101, v100
	v_add_f32_e32 v104, v103, v102
	s_waitcnt lgkmcnt(1)
	v_mfma_f32_32x32x16_bf16 v[64:79], v[234:237], v[160:163], v[64:79]
	v_exp_f32_e32 v102, v106
	v_exp_f32_e32 v103, v107
	ds_read_b128 v[238:241], v212 offset:13056
	v_add_f32_e32 v105, v103, v102
	v_add_f32_e32 v106, v105, v104
	s_waitcnt lgkmcnt(1)
	v_mfma_f32_32x32x16_bf16 v[64:79], v[230:233], v[164:167], v[64:79]
	v_exp_f32_e32 v104, v108
	v_exp_f32_e32 v105, v109
	ds_read_b128 v[234:237], v212 offset:13088
	v_add_f32_e32 v107, v105, v104
	v_add_f32_e32 v127, v107, v106
	s_waitcnt lgkmcnt(1)
	v_mfma_f32_32x32x16_bf16 v[64:79], v[238:241], v[168:171], v[64:79]
	v_exp_f32_e32 v106, v110
	v_exp_f32_e32 v107, v111
	ds_read_b128 v[108:111], v212 offset:13120
	v_add_f32_e32 v189, v107, v106
	v_add_f32_e32 v127, v189, v127
	s_waitcnt lgkmcnt(1)
	v_mfma_f32_32x32x16_bf16 v[64:79], v[234:237], v[172:175], v[64:79]
	ds_read_b128 v[230:233], v212 offset:13152
	v_add_f32_e32 v211, v211, v127
	s_waitcnt lgkmcnt(1)
	v_mfma_f32_32x32x16_bf16 v[64:79], v[108:111], v[176:179], v[64:79]
	s_waitcnt lgkmcnt(0)
	v_mfma_f32_32x32x16_bf16 v[64:79], v[230:233], v[180:183], v[64:79]
	s_and_b64 vcc, exec, s[0:1]
	s_cbranch_vccz .LBB0_742
; __device__ __forceinline__ void mla_unit(const Frame& F, int h, int q0, int key0, int ntiles, int mode, int su) {
;     ...
;     for (int t = 0; t < ntiles; t += 2) { MLA_STEP(sA, sB, t); MLA_STEP(sB, sA, t + 1); }
	v_pk_mul_f32 v[62:63], v[62:63], v[202:203] op_sel_hi:[1,0]
	v_pk_mul_f32 v[60:61], v[60:61], v[202:203] op_sel_hi:[1,0]
	v_pk_mul_f32 v[58:59], v[58:59], v[202:203] op_sel_hi:[1,0]
	v_pk_mul_f32 v[56:57], v[56:57], v[202:203] op_sel_hi:[1,0]
	v_pk_mul_f32 v[54:55], v[54:55], v[202:203] op_sel_hi:[1,0]
	v_pk_mul_f32 v[52:53], v[52:53], v[202:203] op_sel_hi:[1,0]
	v_pk_mul_f32 v[50:51], v[50:51], v[202:203] op_sel_hi:[1,0]
	v_pk_mul_f32 v[48:49], v[48:49], v[202:203] op_sel_hi:[1,0]
	v_pk_mul_f32 v[46:47], v[46:47], v[202:203] op_sel_hi:[1,0]
	v_pk_mul_f32 v[44:45], v[44:45], v[202:203] op_sel_hi:[1,0]
	v_pk_mul_f32 v[42:43], v[42:43], v[202:203] op_sel_hi:[1,0]
	v_pk_mul_f32 v[40:41], v[40:41], v[202:203] op_sel_hi:[1,0]
	v_pk_mul_f32 v[38:39], v[38:39], v[202:203] op_sel_hi:[1,0]
	v_pk_mul_f32 v[36:37], v[36:37], v[202:203] op_sel_hi:[1,0]
	v_pk_mul_f32 v[34:35], v[34:35], v[202:203] op_sel_hi:[1,0]
	v_pk_mul_f32 v[32:33], v[32:33], v[202:203] op_sel_hi:[1,0]
	v_pk_mul_f32 v[30:31], v[30:31], v[202:203] op_sel_hi:[1,0]
	v_pk_mul_f32 v[28:29], v[28:29], v[202:203] op_sel_hi:[1,0]
	v_pk_mul_f32 v[26:27], v[26:27], v[202:203] op_sel_hi:[1,0]
	v_pk_mul_f32 v[24:25], v[24:25], v[202:203] op_sel_hi:[1,0]
	v_pk_mul_f32 v[22:23], v[22:23], v[202:203] op_sel_hi:[1,0]
	v_pk_mul_f32 v[20:21], v[20:21], v[202:203] op_sel_hi:[1,0]
	v_pk_mul_f32 v[18:19], v[18:19], v[202:203] op_sel_hi:[1,0]
	v_pk_mul_f32 v[16:17], v[16:17], v[202:203] op_sel_hi:[1,0]
	v_pk_mul_f32 v[14:15], v[14:15], v[202:203] op_sel_hi:[1,0]
	v_pk_mul_f32 v[12:13], v[12:13], v[202:203] op_sel_hi:[1,0]
	v_pk_mul_f32 v[10:11], v[10:11], v[202:203] op_sel_hi:[1,0]
	v_pk_mul_f32 v[8:9], v[8:9], v[202:203] op_sel_hi:[1,0]
	v_pk_mul_f32 v[6:7], v[6:7], v[202:203] op_sel_hi:[1,0]
	v_pk_mul_f32 v[4:5], v[4:5], v[202:203] op_sel_hi:[1,0]
	v_pk_mul_f32 v[2:3], v[2:3], v[202:203] op_sel_hi:[1,0]
	v_pk_mul_f32 v[0:1], v[0:1], v[202:203] op_sel_hi:[1,0]
	v_sub_f32_e32 v95, v95, v130
	v_sub_f32_e32 v94, v94, v130
	v_sub_f32_e32 v93, v93, v130
	v_sub_f32_e32 v92, v92, v130
	v_sub_f32_e32 v91, v91, v130
	v_sub_f32_e32 v90, v90, v130
	v_sub_f32_e32 v89, v89, v130
	v_sub_f32_e32 v88, v88, v130
	v_sub_f32_e32 v87, v87, v130
	v_sub_f32_e32 v86, v86, v130
	v_sub_f32_e32 v85, v85, v130
	v_sub_f32_e32 v84, v84, v130
	v_sub_f32_e32 v83, v83, v130
	v_sub_f32_e32 v82, v82, v130
	v_sub_f32_e32 v81, v81, v130
	v_sub_f32_e32 v80, v80, v130
	v_sub_f32_e32 v79, v79, v130
	v_sub_f32_e32 v78, v78, v130
	v_sub_f32_e32 v77, v77, v130
	v_sub_f32_e32 v76, v76, v130
	v_sub_f32_e32 v75, v75, v130
	v_sub_f32_e32 v74, v74, v130
	v_sub_f32_e32 v73, v73, v130
	v_sub_f32_e32 v72, v72, v130
	v_sub_f32_e32 v71, v71, v130
	v_sub_f32_e32 v70, v70, v130
	v_sub_f32_e32 v69, v69, v130
	v_sub_f32_e32 v68, v68, v130
	v_sub_f32_e32 v67, v67, v130
	v_sub_f32_e32 v66, v66, v130
	v_sub_f32_e32 v65, v65, v130
	v_sub_f32_e32 v64, v64, v130
.LBB0_742:
	s_mul_i32 s0, s18, 0x5000
	v_add_u32_e32 v127, s0, v210
	ds_read_b64_tr_b16 v[108:109], v127
	ds_read_b64_tr_b16 v[110:111], v127 offset:2560
	v_cvt_pk_bf16_f32 v230, v112, v113
	v_cvt_pk_bf16_f32 v231, v114, v184
	v_cvt_pk_bf16_f32 v232, v185, v186
	v_cvt_pk_bf16_f32 v233, v187, v188
	ds_read_b64_tr_b16 v[184:185], v127 offset:128
	ds_read_b64_tr_b16 v[186:187], v127 offset:2688
	ds_read_b64_tr_b16 v[188:189], v127 offset:192
	ds_read_b64_tr_b16 v[190:191], v127 offset:2752
	ds_read_b64_tr_b16 v[220:221], v127 offset:64
	ds_read_b64_tr_b16 v[222:223], v127 offset:2624
	s_waitcnt lgkmcnt(6)
	v_mfma_f32_32x32x16_bf16 v[48:63], v[108:111], v[230:233], v[48:63]
	ds_read_b64_tr_b16 v[244:245], v127 offset:5120
	ds_read_b64_tr_b16 v[246:247], v127 offset:7680
	v_cvt_pk_bf16_f32 v112, v115, v116
	v_cvt_pk_bf16_f32 v113, v117, v118
	v_cvt_pk_bf16_f32 v114, v119, v120
	v_cvt_pk_bf16_f32 v115, v123, v124
	v_cvt_pk_bf16_f32 v96, v96, v97
	v_cvt_pk_bf16_f32 v97, v98, v99
	s_waitcnt lgkmcnt(6)
	v_mfma_f32_32x32x16_bf16 v[16:31], v[184:187], v[230:233], v[16:31]
	ds_read_b64_tr_b16 v[248:249], v127 offset:5184
	ds_read_b64_tr_b16 v[250:251], v127 offset:7744
	v_cvt_pk_bf16_f32 v98, v121, v122
	v_cvt_pk_bf16_f32 v99, v125, v126
	v_cvt_pk_bf16_f32 v100, v100, v101
	v_cvt_pk_bf16_f32 v101, v102, v103
	v_cvt_pk_bf16_f32 v102, v104, v105
	v_cvt_pk_bf16_f32 v103, v106, v107
	s_waitcnt lgkmcnt(6)
	v_mfma_f32_32x32x16_bf16 v[0:15], v[188:191], v[230:233], v[0:15]
	ds_read_b64_tr_b16 v[108:109], v127 offset:5248
	ds_read_b64_tr_b16 v[110:111], v127 offset:7808
	s_cmp_lt_u32 s20, 64
	s_waitcnt lgkmcnt(6)
	v_mfma_f32_32x32x16_bf16 v[32:47], v[220:223], v[230:233], v[32:47]
	ds_read_b64_tr_b16 v[184:185], v127 offset:5312
	ds_read_b64_tr_b16 v[186:187], v127 offset:7872
	s_waitcnt lgkmcnt(6)
	v_mfma_f32_32x32x16_bf16 v[48:63], v[244:247], v[112:115], v[48:63]
	ds_read_b64_tr_b16 v[188:189], v127 offset:10240
	ds_read_b64_tr_b16 v[190:191], v127 offset:12800
	s_waitcnt lgkmcnt(6)
	v_mfma_f32_32x32x16_bf16 v[32:47], v[248:251], v[112:115], v[32:47]
	ds_read_b64_tr_b16 v[220:221], v127 offset:10304
	ds_read_b64_tr_b16 v[222:223], v127 offset:12864
	s_waitcnt lgkmcnt(6)
	v_mfma_f32_32x32x16_bf16 v[16:31], v[108:111], v[112:115], v[16:31]
	ds_read_b64_tr_b16 v[244:245], v127 offset:10368
	ds_read_b64_tr_b16 v[246:247], v127 offset:12928
	s_waitcnt lgkmcnt(6)
	v_mfma_f32_32x32x16_bf16 v[0:15], v[184:187], v[112:115], v[0:15]
	ds_read_b64_tr_b16 v[248:249], v127 offset:10432
	ds_read_b64_tr_b16 v[250:251], v127 offset:12992
	s_waitcnt lgkmcnt(6)
	v_mfma_f32_32x32x16_bf16 v[48:63], v[188:191], v[96:99], v[48:63]
	ds_read_b64_tr_b16 v[108:109], v127 offset:15360
	ds_read_b64_tr_b16 v[110:111], v127 offset:17920
	s_waitcnt lgkmcnt(6)
	v_mfma_f32_32x32x16_bf16 v[32:47], v[220:223], v[96:99], v[32:47]
	ds_read_b64_tr_b16 v[184:185], v127 offset:15424
	ds_read_b64_tr_b16 v[186:187], v127 offset:17984
	s_waitcnt lgkmcnt(6)
	v_mfma_f32_32x32x16_bf16 v[16:31], v[244:247], v[96:99], v[16:31]
	ds_read_b64_tr_b16 v[188:189], v127 offset:15488
	ds_read_b64_tr_b16 v[190:191], v127 offset:18048
	s_waitcnt lgkmcnt(6)
	v_mfma_f32_32x32x16_bf16 v[0:15], v[248:251], v[96:99], v[0:15]
	ds_read_b64_tr_b16 v[220:221], v127 offset:15552
	ds_read_b64_tr_b16 v[222:223], v127 offset:18112
	s_waitcnt lgkmcnt(6)
	v_mfma_f32_32x32x16_bf16 v[48:63], v[108:111], v[100:103], v[48:63]
	s_waitcnt lgkmcnt(4)
	v_mfma_f32_32x32x16_bf16 v[32:47], v[184:187], v[100:103], v[32:47]
	s_waitcnt vmcnt(0)
	s_waitcnt lgkmcnt(0)
	s_barrier
	s_mul_i32 s40, s17, 0x6400
	v_add_u32_e32 v212, s40, v207
	ds_read_b128 v[244:247], v212
	ds_read_b128 v[248:251], v212 offset:32
	ds_read_b128 v[230:233], v212 offset:64
	v_mfma_f32_32x32x16_bf16 v[16:31], v[188:191], v[100:103], v[16:31]
	v_mfma_f32_32x32x16_bf16 v[0:15], v[220:223], v[100:103], v[0:15]
	s_cbranch_scc0 .LBB0_744
	s_mov_b32 s0, s16
	s_mov_b32 s16, s18
	s_mov_b32 s20, s19
	s_branch .LBB0_724
; __device__ __forceinline__ void mla_unit(const Frame& F, int h, int q0, int key0, int ntiles, int mode, int su) {
;     ...
;     if (mode == 1) { stp[0] = m; stp[64] = l;
; #pragma unroll
;         for (int dt = 0; dt < 4; ++dt)
; #pragma unroll
;             for (int r = 0; r < 16; ++r) stp[(2 + dt * 16 + r) * 64] = O[dt][r];
.LBB0_744:
	s_waitcnt lgkmcnt(0)
	s_lshl_b32 s0, s96, 3
	s_add_i32 s0, s0, s82
	s_mul_hi_i32 s1, s0, 0x4200
	s_mulk_i32 s0, 0x4200
	s_add_u32 s0, s80, s0
	s_addc_u32 s1, s81, s1
	v_ashrrev_i32_e32 v199, 31, v198
	v_lshl_add_u64 v[64:65], v[198:199], 2, s[0:1]
	s_mov_b64 s[0:1], 0x645a4000
	v_lshl_add_u64 v[66:67], v[64:65], 0, s[0:1]
	s_mov_b32 s0, 0x645a4000
	v_add_co_u32_e32 v68, vcc, s0, v64
	s_mov_b32 s0, 0x645a5000
	s_nop 0
	v_addc_co_u32_e32 v69, vcc, 0, v65, vcc
	flat_store_dword v[68:69], v208
	flat_store_dword v[66:67], v211 offset:256
	flat_store_dword v[66:67], v48 offset:512
	flat_store_dword v[66:67], v49 offset:768
	flat_store_dword v[66:67], v50 offset:1024
	flat_store_dword v[66:67], v51 offset:1280
	flat_store_dword v[66:67], v52 offset:1536
	flat_store_dword v[66:67], v53 offset:1792
	flat_store_dword v[66:67], v54 offset:2048
	flat_store_dword v[66:67], v55 offset:2304
	flat_store_dword v[66:67], v56 offset:2560
	flat_store_dword v[66:67], v57 offset:2816
	flat_store_dword v[66:67], v58 offset:3072
	flat_store_dword v[66:67], v59 offset:3328
	flat_store_dword v[66:67], v60 offset:3584
	flat_store_dword v[66:67], v61 offset:3840
	v_add_co_u32_e32 v48, vcc, s0, v64
	s_mov_b32 s0, 0x645a6000
	s_nop 0
	v_addc_co_u32_e32 v49, vcc, 0, v65, vcc
	flat_store_dword v[48:49], v62
	flat_store_dword v[48:49], v63 offset:256
	flat_store_dword v[48:49], v32 offset:512
	flat_store_dword v[48:49], v33 offset:768
	flat_store_dword v[48:49], v34 offset:1024
	flat_store_dword v[48:49], v35 offset:1280
	flat_store_dword v[48:49], v36 offset:1536
	flat_store_dword v[48:49], v37 offset:1792
	flat_store_dword v[48:49], v38 offset:2048
	flat_store_dword v[48:49], v39 offset:2304
	flat_store_dword v[48:49], v40 offset:2560
	flat_store_dword v[48:49], v41 offset:2816
	flat_store_dword v[48:49], v42 offset:3072
	flat_store_dword v[48:49], v43 offset:3328
	flat_store_dword v[48:49], v44 offset:3584
	flat_store_dword v[48:49], v45 offset:3840
	v_add_co_u32_e32 v32, vcc, s0, v64
	s_mov_b32 s0, 0x645a7000
	s_nop 0
	v_addc_co_u32_e32 v33, vcc, 0, v65, vcc
	flat_store_dword v[32:33], v46
	flat_store_dword v[32:33], v47 offset:256
	flat_store_dword v[32:33], v16 offset:512
	flat_store_dword v[32:33], v17 offset:768
	flat_store_dword v[32:33], v18 offset:1024
	flat_store_dword v[32:33], v19 offset:1280
	flat_store_dword v[32:33], v20 offset:1536
	flat_store_dword v[32:33], v21 offset:1792
	flat_store_dword v[32:33], v22 offset:2048
	flat_store_dword v[32:33], v23 offset:2304
	flat_store_dword v[32:33], v24 offset:2560
	flat_store_dword v[32:33], v25 offset:2816
	flat_store_dword v[32:33], v26 offset:3072
	flat_store_dword v[32:33], v27 offset:3328
	flat_store_dword v[32:33], v28 offset:3584
	flat_store_dword v[32:33], v29 offset:3840
	v_add_co_u32_e32 v16, vcc, s0, v64
	s_nop 1
	v_addc_co_u32_e32 v17, vcc, 0, v65, vcc
	flat_store_dword v[16:17], v30
	flat_store_dword v[16:17], v31 offset:256
	flat_store_dword v[16:17], v0 offset:512
	flat_store_dword v[16:17], v1 offset:768
	flat_store_dword v[16:17], v2 offset:1024
	flat_store_dword v[16:17], v3 offset:1280
	flat_store_dword v[16:17], v4 offset:1536
	flat_store_dword v[16:17], v5 offset:1792
	flat_store_dword v[16:17], v6 offset:2048
	flat_store_dword v[16:17], v7 offset:2304
	flat_store_dword v[16:17], v8 offset:2560
	flat_store_dword v[16:17], v9 offset:2816
	flat_store_dword v[16:17], v10 offset:3072
	flat_store_dword v[16:17], v11 offset:3328
	flat_store_dword v[16:17], v12 offset:3584
	flat_store_dword v[16:17], v13 offset:3840
	v_add_co_u32_e32 v0, vcc, 0x645a8000, v64
	s_nop 1
	v_addc_co_u32_e32 v1, vcc, 0, v65, vcc
	flat_store_dword v[0:1], v14
	flat_store_dword v[0:1], v15 offset:256
	s_waitcnt lgkmcnt(0)
	s_barrier
